# as v086, with the P6 panel wait also skipped when phase 5 is not part of the launch
# speedup vs baseline: 1.0056x; 1.0005x over previous
; __global__ void __launch_bounds__(NWAVES * 64, 2) fwd_kernel(Args a) {
;     ...
;     if (IN(6)) for (int rep = 0; rep < NREP(6); ++rep) {
;         pg8::Gemm g{OG, WT4, NTOK, DM, DM}; pg8::StaticOrder S; S.init(NTOK, DM, G, bx);
;         pg8::EpiFinal E{H1B, final_g, a.out, HSS2, CNT, G == 256};
;         pg8::gemm_phase<pg8::EpiFinal, pg8::StaticOrder, GEMM_ALIGN, GEMM_SP2>(lds, g, S, E, wave);
.LBB0_687:
	s_andn2_b64 vcc, exec, s[0:1]
	s_cbranch_vccnz .LBB0_742
	s_cmpk_lg_i32 s88, 0x100
	s_cbranch_scc1 .Lp6_nowait
	v_readlane_b32 s100, v248, 0
	s_cmp_gt_i32 s100, 5
	s_cbranch_scc1 .Lp6_nowait
	s_lshl_b32 s98, s28, 8
	s_add_i32 s98, s98, 4
	v_mov_b32_e32 v236, s98
	s_add_u32 s98, s82, 0x310000
	s_addc_u32 s99, s83, 0
	s_mov_b32 s100, 0
